# v10 + K-loop: s_setprio 1 moved before the pre-MMA barrier and s_setprio 0 after the post-MMA barrier (no SALU between barrier release and the first MFMA)
# speedup vs baseline: 1.0080x; 1.0080x over previous
.LBB0_344:
	s_add_i32 s4, s2, 2
	s_add_u32 s5, s68, s0
	s_addc_u32 s3, s69, s1
	s_add_u32 s33, s86, s0
	s_addc_u32 s35, s87, s1
	s_add_i32 s47, 0, 0x10000
	s_cmp_eq_u32 s21, s2
	s_cselect_b32 s3, s65, s3
	s_cselect_b32 s2, s64, s5
	v_add_u32_e32 v17, s47, v237
	s_cselect_b32 s57, s67, s35
	s_cselect_b32 s56, s66, s33
	s_add_i32 s5, 0, 0x14000
	ds_read_b128 v[134:137], v17
	ds_read_b128 v[138:141], v17 offset:1024
	ds_read_b128 v[142:145], v17 offset:2048
	ds_read_b128 v[146:149], v17 offset:3072
	v_add_u32_e32 v17, s5, v237
	ds_read_b128 v[150:153], v17
	ds_read_b128 v[154:157], v17 offset:1024
	ds_read_b128 v[158:161], v17 offset:2048
	ds_read_b128 v[162:165], v17 offset:3072
	v_lshl_add_u64 v[170:171], s[68:69], 0, v[132:133]
	s_add_i32 m0, s37, 0xc000
	ds_read_b128 v[166:169], v240
	ds_read_b128 v[186:189], v240 offset:1024
	ds_read_b128 v[190:193], v240 offset:2048
	ds_read_b128 v[194:197], v240 offset:3072
	ds_read_b128 v[198:201], v240 offset:4096
	ds_read_b128 v[202:205], v240 offset:5120
	ds_read_b128 v[206:209], v240 offset:6144
	ds_read_b128 v[210:213], v240 offset:7168
	global_load_lds_dwordx4 v[170:171], off
	v_lshl_add_u64 v[170:171], s[68:69], 0, v[18:19]
	s_add_i32 m0, s37, 0xe000
	s_nop 0
	global_load_lds_dwordx4 v[170:171], off
	s_waitcnt vmcnt(8)
	s_waitcnt lgkmcnt(0)
	s_setprio 1
	s_barrier
	v_mfma_f32_16x16x32_bf16 v[8:11], v[134:137], v[166:169], v[8:11]
	v_mfma_f32_16x16x32_bf16 v[12:15], v[142:145], v[166:169], v[12:15]
	v_mfma_f32_16x16x32_bf16 v[28:31], v[134:137], v[190:193], v[28:31]
	v_mfma_f32_16x16x32_bf16 v[32:35], v[142:145], v[190:193], v[32:35]
	v_mfma_f32_16x16x32_bf16 v[36:39], v[134:137], v[198:201], v[36:39]
	v_mfma_f32_16x16x32_bf16 v[44:47], v[142:145], v[198:201], v[44:47]
	v_mfma_f32_16x16x32_bf16 v[80:83], v[134:137], v[206:209], v[80:83]
	v_mfma_f32_16x16x32_bf16 v[88:91], v[142:145], v[206:209], v[88:91]
	v_mfma_f32_16x16x32_bf16 v[8:11], v[138:141], v[186:189], v[8:11]
	v_mfma_f32_16x16x32_bf16 v[12:15], v[146:149], v[186:189], v[12:15]
	v_mfma_f32_16x16x32_bf16 v[28:31], v[138:141], v[194:197], v[28:31]
	v_mfma_f32_16x16x32_bf16 v[32:35], v[146:149], v[194:197], v[32:35]
	v_mfma_f32_16x16x32_bf16 v[36:39], v[138:141], v[202:205], v[36:39]
	v_mfma_f32_16x16x32_bf16 v[44:47], v[146:149], v[202:205], v[44:47]
	v_mfma_f32_16x16x32_bf16 v[80:83], v[138:141], v[210:213], v[80:83]
	v_mfma_f32_16x16x32_bf16 v[88:91], v[146:149], v[210:213], v[88:91]
	v_mfma_f32_16x16x32_bf16 v[0:3], v[150:153], v[166:169], v[0:3]
	v_mfma_f32_16x16x32_bf16 v[4:7], v[158:161], v[166:169], v[4:7]
	v_mfma_f32_16x16x32_bf16 v[20:23], v[150:153], v[190:193], v[20:23]
	v_mfma_f32_16x16x32_bf16 v[24:27], v[158:161], v[190:193], v[24:27]
	v_mfma_f32_16x16x32_bf16 v[40:43], v[150:153], v[198:201], v[40:43]
	v_mfma_f32_16x16x32_bf16 v[48:51], v[158:161], v[198:201], v[48:51]
	v_mfma_f32_16x16x32_bf16 v[60:63], v[150:153], v[206:209], v[60:63]
	v_mfma_f32_16x16x32_bf16 v[64:67], v[158:161], v[206:209], v[64:67]
	v_mfma_f32_16x16x32_bf16 v[0:3], v[154:157], v[186:189], v[0:3]
	v_mfma_f32_16x16x32_bf16 v[4:7], v[162:165], v[186:189], v[4:7]
	v_mfma_f32_16x16x32_bf16 v[20:23], v[154:157], v[194:197], v[20:23]
	v_mfma_f32_16x16x32_bf16 v[24:27], v[162:165], v[194:197], v[24:27]
	v_mfma_f32_16x16x32_bf16 v[40:43], v[154:157], v[202:205], v[40:43]
	v_mfma_f32_16x16x32_bf16 v[48:51], v[162:165], v[202:205], v[48:51]
	v_mfma_f32_16x16x32_bf16 v[60:63], v[154:157], v[210:213], v[60:63]
	v_mfma_f32_16x16x32_bf16 v[64:67], v[162:165], v[210:213], v[64:67]
	s_barrier
	s_setprio 0
	s_add_i32 s33, s47, s17
	v_lshl_add_u64 v[170:171], s[56:57], 0, v[174:175]
	s_mov_b32 m0, s33
	ds_read_b128 v[166:169], v240 offset:16384
	ds_read_b128 v[186:189], v240 offset:17408
	ds_read_b128 v[190:193], v240 offset:18432
	ds_read_b128 v[194:197], v240 offset:19456
	ds_read_b128 v[198:201], v240 offset:20480
	ds_read_b128 v[202:205], v240 offset:21504
	ds_read_b128 v[206:209], v240 offset:22528
	ds_read_b128 v[210:213], v240 offset:23552
	global_load_lds_dwordx4 v[170:171], off
	s_add_i32 m0, s33, 0x2000
	v_lshl_add_u64 v[214:215], s[56:57], 0, v[178:179]
	s_add_u32 s56, s56, s36
	s_addc_u32 s57, s57, 0
	s_add_i32 s5, s5, s17
	global_load_lds_dwordx4 v[214:215], off
	v_lshl_add_u64 v[216:217], s[56:57], 0, v[174:175]
	s_mov_b32 m0, s5
	v_lshl_add_u64 v[224:225], s[56:57], 0, v[178:179]
	global_load_lds_dwordx4 v[216:217], off
	s_add_i32 m0, s5, 0x2000
	v_lshl_add_u64 v[226:227], s[2:3], 0, v[172:173]
	global_load_lds_dwordx4 v[224:225], off
	s_mov_b32 m0, s37
	v_lshl_add_u64 v[242:243], s[2:3], 0, v[176:177]
	global_load_lds_dwordx4 v[226:227], off
	s_mov_b32 m0, s45
	s_nop 0
	global_load_lds_dwordx4 v[242:243], off
	s_waitcnt vmcnt(8)
	s_waitcnt lgkmcnt(0)
	s_setprio 1
	s_barrier
	v_mfma_f32_16x16x32_bf16 v[68:71], v[134:137], v[166:169], v[68:71]
	v_mfma_f32_16x16x32_bf16 v[72:75], v[142:145], v[166:169], v[72:75]
	v_mfma_f32_16x16x32_bf16 v[92:95], v[134:137], v[190:193], v[92:95]
	v_mfma_f32_16x16x32_bf16 v[96:99], v[142:145], v[190:193], v[96:99]
	v_mfma_f32_16x16x32_bf16 v[108:111], v[134:137], v[198:201], v[108:111]
	v_mfma_f32_16x16x32_bf16 v[112:115], v[142:145], v[198:201], v[112:115]
	v_mfma_f32_16x16x32_bf16 v[124:127], v[134:137], v[206:209], v[124:127]
	v_mfma_f32_16x16x32_bf16 v[128:131], v[142:145], v[206:209], v[128:131]
	v_mfma_f32_16x16x32_bf16 v[68:71], v[138:141], v[186:189], v[68:71]
	v_mfma_f32_16x16x32_bf16 v[72:75], v[146:149], v[186:189], v[72:75]
	v_mfma_f32_16x16x32_bf16 v[92:95], v[138:141], v[194:197], v[92:95]
	v_mfma_f32_16x16x32_bf16 v[96:99], v[146:149], v[194:197], v[96:99]
	v_mfma_f32_16x16x32_bf16 v[108:111], v[138:141], v[202:205], v[108:111]
	v_mfma_f32_16x16x32_bf16 v[112:115], v[146:149], v[202:205], v[112:115]
	v_mfma_f32_16x16x32_bf16 v[124:127], v[138:141], v[210:213], v[124:127]
	v_mfma_f32_16x16x32_bf16 v[128:131], v[146:149], v[210:213], v[128:131]
	v_mfma_f32_16x16x32_bf16 v[52:55], v[150:153], v[166:169], v[52:55]
	v_mfma_f32_16x16x32_bf16 v[56:59], v[158:161], v[166:169], v[56:59]
	v_mfma_f32_16x16x32_bf16 v[76:79], v[150:153], v[190:193], v[76:79]
	v_mfma_f32_16x16x32_bf16 v[84:87], v[158:161], v[190:193], v[84:87]
	v_mfma_f32_16x16x32_bf16 v[100:103], v[150:153], v[198:201], v[100:103]
	v_mfma_f32_16x16x32_bf16 v[104:107], v[158:161], v[198:201], v[104:107]
	v_mfma_f32_16x16x32_bf16 v[116:119], v[150:153], v[206:209], v[116:119]
	v_mfma_f32_16x16x32_bf16 v[120:123], v[158:161], v[206:209], v[120:123]
	v_mfma_f32_16x16x32_bf16 v[52:55], v[154:157], v[186:189], v[52:55]
	v_mfma_f32_16x16x32_bf16 v[56:59], v[162:165], v[186:189], v[56:59]
	v_mfma_f32_16x16x32_bf16 v[76:79], v[154:157], v[194:197], v[76:79]
	v_mfma_f32_16x16x32_bf16 v[84:87], v[162:165], v[194:197], v[84:87]
	v_mfma_f32_16x16x32_bf16 v[100:103], v[154:157], v[202:205], v[100:103]
	v_mfma_f32_16x16x32_bf16 v[104:107], v[162:165], v[202:205], v[104:107]
	v_mfma_f32_16x16x32_bf16 v[116:119], v[154:157], v[210:213], v[116:119]
	v_mfma_f32_16x16x32_bf16 v[120:123], v[162:165], v[210:213], v[120:123]
	s_barrier
	s_setprio 0
	s_add_i32 s5, 0, 0x18000
	v_add_u32_e32 v17, s5, v237
	s_add_i32 s33, 0, 0x1c000
	ds_read_b128 v[134:137], v17
	ds_read_b128 v[138:141], v17 offset:1024
	ds_read_b128 v[142:145], v17 offset:2048
	ds_read_b128 v[146:149], v17 offset:3072
	v_add_u32_e32 v17, s33, v237
	ds_read_b128 v[150:153], v17
	ds_read_b128 v[154:157], v17 offset:1024
	ds_read_b128 v[158:161], v17 offset:2048
	ds_read_b128 v[162:165], v17 offset:3072
	s_add_u32 s2, s2, s36
	s_addc_u32 s3, s3, 0
	s_mov_b32 m0, s26
	v_lshl_add_u64 v[244:245], s[2:3], 0, v[172:173]
	ds_read_b128 v[166:169], v240 offset:32768
	ds_read_b128 v[186:189], v240 offset:33792
	ds_read_b128 v[190:193], v240 offset:34816
	ds_read_b128 v[194:197], v240 offset:35840
	ds_read_b128 v[198:201], v240 offset:36864
	ds_read_b128 v[202:205], v240 offset:37888
	ds_read_b128 v[206:209], v240 offset:38912
	ds_read_b128 v[210:213], v240 offset:39936
	global_load_lds_dwordx4 v[244:245], off
	v_lshl_add_u64 v[244:245], s[2:3], 0, v[176:177]
	s_mov_b32 m0, s27
	s_nop 0
	global_load_lds_dwordx4 v[244:245], off
	s_waitcnt vmcnt(8)
	s_waitcnt lgkmcnt(0)
	s_setprio 1
	s_barrier
	v_mfma_f32_16x16x32_bf16 v[8:11], v[134:137], v[166:169], v[8:11]
	v_mfma_f32_16x16x32_bf16 v[12:15], v[142:145], v[166:169], v[12:15]
	v_mfma_f32_16x16x32_bf16 v[28:31], v[134:137], v[190:193], v[28:31]
	v_mfma_f32_16x16x32_bf16 v[32:35], v[142:145], v[190:193], v[32:35]
	v_mfma_f32_16x16x32_bf16 v[36:39], v[134:137], v[198:201], v[36:39]
	v_mfma_f32_16x16x32_bf16 v[44:47], v[142:145], v[198:201], v[44:47]
	v_mfma_f32_16x16x32_bf16 v[80:83], v[134:137], v[206:209], v[80:83]
	v_mfma_f32_16x16x32_bf16 v[88:91], v[142:145], v[206:209], v[88:91]
	v_mfma_f32_16x16x32_bf16 v[8:11], v[138:141], v[186:189], v[8:11]
	v_mfma_f32_16x16x32_bf16 v[12:15], v[146:149], v[186:189], v[12:15]
	v_mfma_f32_16x16x32_bf16 v[28:31], v[138:141], v[194:197], v[28:31]
	v_mfma_f32_16x16x32_bf16 v[32:35], v[146:149], v[194:197], v[32:35]
	v_mfma_f32_16x16x32_bf16 v[36:39], v[138:141], v[202:205], v[36:39]
	v_mfma_f32_16x16x32_bf16 v[44:47], v[146:149], v[202:205], v[44:47]
	v_mfma_f32_16x16x32_bf16 v[80:83], v[138:141], v[210:213], v[80:83]
	v_mfma_f32_16x16x32_bf16 v[88:91], v[146:149], v[210:213], v[88:91]
	v_mfma_f32_16x16x32_bf16 v[0:3], v[150:153], v[166:169], v[0:3]
	v_mfma_f32_16x16x32_bf16 v[4:7], v[158:161], v[166:169], v[4:7]
	v_mfma_f32_16x16x32_bf16 v[20:23], v[150:153], v[190:193], v[20:23]
	v_mfma_f32_16x16x32_bf16 v[24:27], v[158:161], v[190:193], v[24:27]
	v_mfma_f32_16x16x32_bf16 v[40:43], v[150:153], v[198:201], v[40:43]
	v_mfma_f32_16x16x32_bf16 v[48:51], v[158:161], v[198:201], v[48:51]
	v_mfma_f32_16x16x32_bf16 v[60:63], v[150:153], v[206:209], v[60:63]
	v_mfma_f32_16x16x32_bf16 v[64:67], v[158:161], v[206:209], v[64:67]
	v_mfma_f32_16x16x32_bf16 v[0:3], v[154:157], v[186:189], v[0:3]
	v_mfma_f32_16x16x32_bf16 v[4:7], v[162:165], v[186:189], v[4:7]
	v_mfma_f32_16x16x32_bf16 v[20:23], v[154:157], v[194:197], v[20:23]
	v_mfma_f32_16x16x32_bf16 v[24:27], v[162:165], v[194:197], v[24:27]
	v_mfma_f32_16x16x32_bf16 v[40:43], v[154:157], v[202:205], v[40:43]
	v_mfma_f32_16x16x32_bf16 v[48:51], v[162:165], v[202:205], v[48:51]
	v_mfma_f32_16x16x32_bf16 v[60:63], v[154:157], v[210:213], v[60:63]
	v_mfma_f32_16x16x32_bf16 v[64:67], v[162:165], v[210:213], v[64:67]
	s_barrier
	s_setprio 0
	s_add_i32 s2, s5, s17
	v_lshl_add_u64 v[170:171], v[170:171], 0, s[6:7]
	s_mov_b32 m0, s2
	ds_read_b128 v[166:169], v240 offset:49152
	ds_read_b128 v[186:189], v240 offset:50176
	ds_read_b128 v[190:193], v240 offset:51200
	ds_read_b128 v[194:197], v240 offset:52224
	ds_read_b128 v[198:201], v240 offset:53248
	ds_read_b128 v[202:205], v240 offset:54272
	ds_read_b128 v[206:209], v240 offset:55296
	ds_read_b128 v[210:213], v240 offset:56320
	global_load_lds_dwordx4 v[170:171], off
	v_lshl_add_u64 v[170:171], v[214:215], 0, s[6:7]
	s_add_i32 m0, s2, 0x2000
	s_add_i32 s2, s33, s17
	global_load_lds_dwordx4 v[170:171], off
	v_lshl_add_u64 v[170:171], v[216:217], 0, s[6:7]
	s_mov_b32 m0, s2
	s_nop 0
	global_load_lds_dwordx4 v[170:171], off
	v_lshl_add_u64 v[170:171], v[224:225], 0, s[6:7]
	s_add_i32 m0, s2, 0x2000
	s_nop 0
	global_load_lds_dwordx4 v[170:171], off
	v_lshl_add_u64 v[170:171], v[226:227], 0, s[6:7]
	s_mov_b32 m0, s63
	s_nop 0
	global_load_lds_dwordx4 v[170:171], off
	v_lshl_add_u64 v[170:171], v[242:243], 0, s[6:7]
	s_mov_b32 m0, s20
	s_nop 0
	global_load_lds_dwordx4 v[170:171], off
	s_waitcnt vmcnt(8)
	s_waitcnt lgkmcnt(0)
	s_setprio 1
	s_barrier
	v_mfma_f32_16x16x32_bf16 v[68:71], v[134:137], v[166:169], v[68:71]
	v_mfma_f32_16x16x32_bf16 v[72:75], v[142:145], v[166:169], v[72:75]
	v_mfma_f32_16x16x32_bf16 v[92:95], v[134:137], v[190:193], v[92:95]
	v_mfma_f32_16x16x32_bf16 v[96:99], v[142:145], v[190:193], v[96:99]
	v_mfma_f32_16x16x32_bf16 v[108:111], v[134:137], v[198:201], v[108:111]
	v_mfma_f32_16x16x32_bf16 v[112:115], v[142:145], v[198:201], v[112:115]
	v_mfma_f32_16x16x32_bf16 v[124:127], v[134:137], v[206:209], v[124:127]
	v_mfma_f32_16x16x32_bf16 v[128:131], v[142:145], v[206:209], v[128:131]
	v_mfma_f32_16x16x32_bf16 v[68:71], v[138:141], v[186:189], v[68:71]
	v_mfma_f32_16x16x32_bf16 v[72:75], v[146:149], v[186:189], v[72:75]
	v_mfma_f32_16x16x32_bf16 v[92:95], v[138:141], v[194:197], v[92:95]
	v_mfma_f32_16x16x32_bf16 v[96:99], v[146:149], v[194:197], v[96:99]
	v_mfma_f32_16x16x32_bf16 v[108:111], v[138:141], v[202:205], v[108:111]
	v_mfma_f32_16x16x32_bf16 v[112:115], v[146:149], v[202:205], v[112:115]
	v_mfma_f32_16x16x32_bf16 v[124:127], v[138:141], v[210:213], v[124:127]
	v_mfma_f32_16x16x32_bf16 v[128:131], v[146:149], v[210:213], v[128:131]
	v_mfma_f32_16x16x32_bf16 v[52:55], v[150:153], v[166:169], v[52:55]
	v_mfma_f32_16x16x32_bf16 v[56:59], v[158:161], v[166:169], v[56:59]
	v_mfma_f32_16x16x32_bf16 v[76:79], v[150:153], v[190:193], v[76:79]
	v_mfma_f32_16x16x32_bf16 v[84:87], v[158:161], v[190:193], v[84:87]
	v_mfma_f32_16x16x32_bf16 v[100:103], v[150:153], v[198:201], v[100:103]
	v_mfma_f32_16x16x32_bf16 v[104:107], v[158:161], v[198:201], v[104:107]
	v_mfma_f32_16x16x32_bf16 v[116:119], v[150:153], v[206:209], v[116:119]
	v_mfma_f32_16x16x32_bf16 v[120:123], v[158:161], v[206:209], v[120:123]
	v_mfma_f32_16x16x32_bf16 v[52:55], v[154:157], v[186:189], v[52:55]
	v_mfma_f32_16x16x32_bf16 v[56:59], v[162:165], v[186:189], v[56:59]
	v_mfma_f32_16x16x32_bf16 v[76:79], v[154:157], v[194:197], v[76:79]
	v_mfma_f32_16x16x32_bf16 v[84:87], v[162:165], v[194:197], v[84:87]
	v_mfma_f32_16x16x32_bf16 v[100:103], v[154:157], v[202:205], v[100:103]
	v_mfma_f32_16x16x32_bf16 v[104:107], v[162:165], v[202:205], v[104:107]
	v_mfma_f32_16x16x32_bf16 v[116:119], v[154:157], v[210:213], v[116:119]
	v_mfma_f32_16x16x32_bf16 v[120:123], v[162:165], v[210:213], v[120:123]
	s_barrier
	s_setprio 0
	s_add_u32 s0, s0, 0x100
	s_addc_u32 s1, s1, 0
	v_lshl_add_u64 v[132:133], v[132:133], 0, s[8:9]
	v_lshl_add_u64 v[18:19], v[18:19], 0, s[8:9]
	s_cmp_ge_u32 s4, s62
	s_mov_b32 s2, s4
	s_cbranch_scc0 .LBB0_344
	v_readlane_b32 s0, v253, 40
	v_readlane_b32 s1, v253, 41
	s_and_b64 vcc, exec, s[0:1]
	s_cbranch_vccz .LBB0_347
	s_barrier
